# FFN-up glds gemm8: SGPR allocation kept inside the original body's clobber set, LDS quiesced (vmcnt(0)+barrier) at phase end
# speedup vs baseline: 1.0786x; 1.0015x over previous
.LBB0_1140:
	s_cmp_lt_i32 s88, 10
	s_cselect_b64 s[6:7], -1, 0
	s_and_b64 s[4:5], s[6:7], s[4:5]
	s_andn2_b64 vcc, exec, s[4:5]
	s_cbranch_vccnz .LBB0_1148
	s_cmpk_gt_i32 s2, 0x2bf
	s_cbranch_scc1 .LBB0_1148
	s_load_dword s9, s[0:1], 0x120
	v_readfirstlane_b32 s42, v205
	v_and_b32_e32 v192, 15, v204
	v_bfe_u32 v193, v204, 4, 2
	v_lshrrev_b32_e32 v194, 8, v204
	v_bfe_u32 v195, v204, 6, 2
	v_bfe_u32 v196, v204, 1, 3
	v_xor_b32_e32 v197, v193, v196
	v_xor_b32_e32 v198, 4, v197
	v_lshlrev_b32_e32 v197, 4, v197
	v_lshlrev_b32_e32 v198, 4, v198
	v_lshlrev_b32_e32 v199, 14, v194
	v_lshl_add_u32 v199, v192, 7, v199
	v_add_u32_e32 v242, v199, v197
	v_add_u32_e32 v243, v199, v198
	v_lshlrev_b32_e32 v199, 13, v195
	v_lshl_add_u32 v199, v192, 7, v199
	v_add_u32_e32 v199, 0x8000, v199
	v_add_u32_e32 v244, v199, v197
	v_add_u32_e32 v245, v199, v198
	v_add_u32_e32 v246, 0x10000, v242
	v_add_u32_e32 v248, 0x10000, v244
	v_add_u32_e32 v247, 0x10000, v243
	v_add_u32_e32 v249, 0x10000, v245
	v_lshrrev_b32_e32 v199, 3, v204
	v_and_b32_e32 v200, 7, v204
	v_bfe_u32 v201, v204, 4, 3
	v_xor_b32_e32 v200, v200, v201
	v_lshlrev_b32_e32 v200, 4, v200
	v_lshl_add_u32 v238, v199, 11, v200
	v_add_u32_e32 v239, 0x20000, v238
	v_add_u32_e32 v240, 0x40000, v238
	v_add_u32_e32 v241, 0x60000, v238
	s_lshl_b32 s42, s42, 10
	s_mov_b32 s8, s2
	s_and_b32 s44, s8, 7
	s_mulk_i32 s44, 0x58
	s_lshr_b32 s45, s8, 3
	s_add_i32 s44, s44, s45
	s_cmpk_ge_i32 s44, 176
	s_cselect_b32 s45, 1, 0
	s_cmpk_ge_i32 s44, 352
	s_cselect_b32 s98, 1, 0
	s_add_i32 s45, s45, s98
	s_cmpk_ge_i32 s44, 528
	s_cselect_b32 s98, 1, 0
	s_add_i32 s45, s45, s98
	s_mul_i32 s98, s45, 176
	s_sub_i32 s44, s44, s98
	s_and_b32 s98, s44, 7
	s_lshl_b32 s45, s45, 3
	s_add_i32 s45, s45, s98
	s_lshl_b32 s14, s45, 8
	s_lshr_b32 s44, s44, 3
	s_lshl_b32 s15, s44, 8
	s_mul_i32 s44, s14, 0x800
	s_add_u32 s44, s44, 0x8a44000
	s_add_u32 s10, s34, s44
	s_addc_u32 s11, s35, 0
	s_mul_i32 s44, s15, 0x800
	s_add_u32 s44, s44, 0x7a0000
	s_add_u32 s12, s34, s44
	s_addc_u32 s13, s35, 0
	s_waitcnt vmcnt(0) lgkmcnt(0)
	s_barrier
	s_add_u32 m0, s42, 0x0
	s_nop 0
	global_load_lds_dwordx4 v238, s[10:11]
	s_add_u32 m0, s42, 0x2000
	s_nop 0
	global_load_lds_dwordx4 v239, s[10:11]
	s_add_u32 m0, s42, 0x4000
	s_nop 0
	global_load_lds_dwordx4 v240, s[10:11]
	s_add_u32 m0, s42, 0x6000
	s_nop 0
	global_load_lds_dwordx4 v241, s[10:11]
	s_add_u32 m0, s42, 0x8000
	s_nop 0
	global_load_lds_dwordx4 v238, s[12:13]
	s_add_u32 m0, s42, 0xa000
	s_nop 0
	global_load_lds_dwordx4 v239, s[12:13]
	s_add_u32 m0, s42, 0xc000
	s_nop 0
	global_load_lds_dwordx4 v240, s[12:13]
	s_add_u32 m0, s42, 0xe000
	s_nop 0
	global_load_lds_dwordx4 v241, s[12:13]
	s_waitcnt vmcnt(0)
.Lgl_tile_ffnup0:
	s_add_i32 s43, s8, s9
	s_cmpk_lt_i32 s43, 704
	s_cselect_b64 s[26:27], 0, -1
	s_cbranch_scc0 .Lgl_nonext_ffnup0
	s_and_b32 s44, s43, 7
	s_mulk_i32 s44, 0x58
	s_lshr_b32 s45, s43, 3
	s_add_i32 s44, s44, s45
	s_cmpk_ge_i32 s44, 176
	s_cselect_b32 s45, 1, 0
	s_cmpk_ge_i32 s44, 352
	s_cselect_b32 s98, 1, 0
	s_add_i32 s45, s45, s98
	s_cmpk_ge_i32 s44, 528
	s_cselect_b32 s98, 1, 0
	s_add_i32 s45, s45, s98
	s_mul_i32 s98, s45, 176
	s_sub_i32 s44, s44, s98
	s_and_b32 s98, s44, 7
	s_lshl_b32 s45, s45, 3
	s_add_i32 s45, s45, s98
	s_lshl_b32 s20, s45, 8
	s_lshr_b32 s44, s44, 3
	s_lshl_b32 s21, s44, 8
	s_mul_i32 s44, s20, 0x800
	s_add_u32 s44, s44, 0x8a44000
	s_add_u32 s22, s34, s44
	s_addc_u32 s23, s35, 0
	s_mul_i32 s44, s21, 0x800
	s_add_u32 s44, s44, 0x7a0000
	s_add_u32 s24, s34, s44
	s_addc_u32 s25, s35, 0
	s_branch .Lgl_havenext_ffnup0
.Lgl_nonext_ffnup0:
	s_mov_b32 s20, s14
	s_mov_b32 s21, s15
	s_mov_b64 s[22:23], s[10:11]
	s_mov_b64 s[24:25], s[12:13]
.Lgl_havenext_ffnup0:
	v_mov_b32_e32 v0, 0
	v_mov_b32_e32 v1, 0
	v_mov_b32_e32 v2, 0
	v_mov_b32_e32 v3, 0
	v_mov_b32_e32 v4, 0
	v_mov_b32_e32 v5, 0
	v_mov_b32_e32 v6, 0
	v_mov_b32_e32 v7, 0
	v_mov_b32_e32 v8, 0
	v_mov_b32_e32 v9, 0
	v_mov_b32_e32 v10, 0
	v_mov_b32_e32 v11, 0
	v_mov_b32_e32 v12, 0
	v_mov_b32_e32 v13, 0
	v_mov_b32_e32 v14, 0
	v_mov_b32_e32 v15, 0
	v_mov_b32_e32 v16, 0
	v_mov_b32_e32 v17, 0
	v_mov_b32_e32 v18, 0
	v_mov_b32_e32 v19, 0
	v_mov_b32_e32 v20, 0
	v_mov_b32_e32 v21, 0
	v_mov_b32_e32 v22, 0
	v_mov_b32_e32 v23, 0
	v_mov_b32_e32 v24, 0
	v_mov_b32_e32 v25, 0
	v_mov_b32_e32 v26, 0
	v_mov_b32_e32 v27, 0
	v_mov_b32_e32 v28, 0
	v_mov_b32_e32 v29, 0
	v_mov_b32_e32 v30, 0
	v_mov_b32_e32 v31, 0
	v_mov_b32_e32 v32, 0
	v_mov_b32_e32 v33, 0
	v_mov_b32_e32 v34, 0
	v_mov_b32_e32 v35, 0
	v_mov_b32_e32 v36, 0
	v_mov_b32_e32 v37, 0
	v_mov_b32_e32 v38, 0
	v_mov_b32_e32 v39, 0
	v_mov_b32_e32 v40, 0
	v_mov_b32_e32 v41, 0
	v_mov_b32_e32 v42, 0
	v_mov_b32_e32 v43, 0
	v_mov_b32_e32 v44, 0
	v_mov_b32_e32 v45, 0
	v_mov_b32_e32 v46, 0
	v_mov_b32_e32 v47, 0
	v_mov_b32_e32 v48, 0
	v_mov_b32_e32 v49, 0
	v_mov_b32_e32 v50, 0
	v_mov_b32_e32 v51, 0
	v_mov_b32_e32 v52, 0
	v_mov_b32_e32 v53, 0
	v_mov_b32_e32 v54, 0
	v_mov_b32_e32 v55, 0
	v_mov_b32_e32 v56, 0
	v_mov_b32_e32 v57, 0
	v_mov_b32_e32 v58, 0
	v_mov_b32_e32 v59, 0
	v_mov_b32_e32 v60, 0
	v_mov_b32_e32 v61, 0
	v_mov_b32_e32 v62, 0
	v_mov_b32_e32 v63, 0
	v_mov_b32_e32 v64, 0
	v_mov_b32_e32 v65, 0
	v_mov_b32_e32 v66, 0
	v_mov_b32_e32 v67, 0
	v_mov_b32_e32 v68, 0
	v_mov_b32_e32 v69, 0
	v_mov_b32_e32 v70, 0
	v_mov_b32_e32 v71, 0
	v_mov_b32_e32 v72, 0
	v_mov_b32_e32 v73, 0
	v_mov_b32_e32 v74, 0
	v_mov_b32_e32 v75, 0
	v_mov_b32_e32 v76, 0
	v_mov_b32_e32 v77, 0
	v_mov_b32_e32 v78, 0
	v_mov_b32_e32 v79, 0
	v_mov_b32_e32 v80, 0
	v_mov_b32_e32 v81, 0
	v_mov_b32_e32 v82, 0
	v_mov_b32_e32 v83, 0
	v_mov_b32_e32 v84, 0
	v_mov_b32_e32 v85, 0
	v_mov_b32_e32 v86, 0
	v_mov_b32_e32 v87, 0
	v_mov_b32_e32 v88, 0
	v_mov_b32_e32 v89, 0
	v_mov_b32_e32 v90, 0
	v_mov_b32_e32 v91, 0
	v_mov_b32_e32 v92, 0
	v_mov_b32_e32 v93, 0
	v_mov_b32_e32 v94, 0
	v_mov_b32_e32 v95, 0
	v_mov_b32_e32 v96, 0
	v_mov_b32_e32 v97, 0
	v_mov_b32_e32 v98, 0
	v_mov_b32_e32 v99, 0
	v_mov_b32_e32 v100, 0
	v_mov_b32_e32 v101, 0
	v_mov_b32_e32 v102, 0
	v_mov_b32_e32 v103, 0
	v_mov_b32_e32 v104, 0
	v_mov_b32_e32 v105, 0
	v_mov_b32_e32 v106, 0
	v_mov_b32_e32 v107, 0
	v_mov_b32_e32 v108, 0
	v_mov_b32_e32 v109, 0
	v_mov_b32_e32 v110, 0
	v_mov_b32_e32 v111, 0
	v_mov_b32_e32 v112, 0
	v_mov_b32_e32 v113, 0
	v_mov_b32_e32 v114, 0
	v_mov_b32_e32 v115, 0
	v_mov_b32_e32 v116, 0
	v_mov_b32_e32 v117, 0
	v_mov_b32_e32 v118, 0
	v_mov_b32_e32 v119, 0
	v_mov_b32_e32 v120, 0
	v_mov_b32_e32 v121, 0
	v_mov_b32_e32 v122, 0
	v_mov_b32_e32 v123, 0
	v_mov_b32_e32 v124, 0
	v_mov_b32_e32 v125, 0
	v_mov_b32_e32 v126, 0
	v_mov_b32_e32 v127, 0
	v_mov_b32_e32 v184, 0
	v_mov_b32_e32 v185, 0
	v_mov_b32_e32 v186, 0
	v_mov_b32_e32 v187, 0
	v_mov_b32_e32 v188, 0
	v_mov_b32_e32 v189, 0
	v_mov_b32_e32 v190, 0
	v_mov_b32_e32 v191, 0
	v_mov_b32_e32 v222, 0
	v_mov_b32_e32 v223, 0
	v_mov_b32_e32 v224, 0
	v_mov_b32_e32 v225, 0
	v_mov_b32_e32 v226, 0
	v_mov_b32_e32 v227, 0
	v_mov_b32_e32 v228, 0
	v_mov_b32_e32 v229, 0
	v_mov_b32_e32 v230, 0
	v_mov_b32_e32 v231, 0
	v_mov_b32_e32 v232, 0
	v_mov_b32_e32 v233, 0
	v_mov_b32_e32 v234, 0
	v_mov_b32_e32 v235, 0
	v_mov_b32_e32 v236, 0
	v_mov_b32_e32 v237, 0
	s_add_u32 s28, s10, 0x80
	s_addc_u32 s29, s11, 0
	s_add_u32 s30, s12, 0x80
	s_addc_u32 s31, s13, 0
	s_mov_b32 s33, 0
	s_waitcnt vmcnt(8)
	s_barrier
	s_branch .Lgl_kentry_ffnup0

.Lgl_kentry_ffnup0:
	s_setprio 1
	ds_read_b128 v[206:209], v244
	ds_read_b128 v[210:213], v244 offset:2048
	ds_read_b128 v[214:217], v244 offset:4096
	ds_read_b128 v[218:221], v244 offset:6144
	ds_read_b128 v[128:131], v242
	ds_read_b128 v[132:135], v242 offset:2048
	ds_read_b128 v[136:139], v242 offset:4096
	ds_read_b128 v[140:143], v242 offset:6144
	ds_read_b128 v[144:147], v242 offset:8192
	ds_read_b128 v[148:151], v242 offset:10240
	ds_read_b128 v[152:155], v242 offset:12288
	ds_read_b128 v[156:159], v242 offset:14336
	v_mfma_f32_16x16x32_bf16 v[96:99], v[222:225], v[184:187], v[96:99]
	v_mfma_f32_16x16x32_bf16 v[100:103], v[226:229], v[184:187], v[100:103]
	v_mfma_f32_16x16x32_bf16 v[104:107], v[230:233], v[184:187], v[104:107]
	v_mfma_f32_16x16x32_bf16 v[108:111], v[234:237], v[184:187], v[108:111]
	v_mfma_f32_16x16x32_bf16 v[112:115], v[222:225], v[188:191], v[112:115]
	v_mfma_f32_16x16x32_bf16 v[116:119], v[226:229], v[188:191], v[116:119]
	v_mfma_f32_16x16x32_bf16 v[120:123], v[230:233], v[188:191], v[120:123]
	v_mfma_f32_16x16x32_bf16 v[124:127], v[234:237], v[188:191], v[124:127]
	s_waitcnt lgkmcnt(7)
	v_mfma_f32_16x16x32_bf16 v[0:3], v[206:209], v[128:131], v[0:3]
	v_mfma_f32_16x16x32_bf16 v[4:7], v[210:213], v[128:131], v[4:7]
	v_mfma_f32_16x16x32_bf16 v[8:11], v[214:217], v[128:131], v[8:11]
	v_mfma_f32_16x16x32_bf16 v[12:15], v[218:221], v[128:131], v[12:15]
	s_add_u32 m0, s42, 0x10000
	s_nop 0
	global_load_lds_dwordx4 v238, s[28:29]
	s_add_u32 m0, s42, 0x12000
	s_nop 0
	global_load_lds_dwordx4 v239, s[28:29]
	ds_read_b128 v[222:225], v245
	ds_read_b128 v[226:229], v245 offset:2048
	s_waitcnt lgkmcnt(8)
	v_mfma_f32_16x16x32_bf16 v[16:19], v[206:209], v[132:135], v[16:19]
	v_mfma_f32_16x16x32_bf16 v[20:23], v[210:213], v[132:135], v[20:23]
	v_mfma_f32_16x16x32_bf16 v[24:27], v[214:217], v[132:135], v[24:27]
	v_mfma_f32_16x16x32_bf16 v[28:31], v[218:221], v[132:135], v[28:31]
	s_add_u32 m0, s42, 0x14000
	s_nop 0
	global_load_lds_dwordx4 v240, s[28:29]
	s_add_u32 m0, s42, 0x16000
	s_nop 0
	global_load_lds_dwordx4 v241, s[28:29]
	ds_read_b128 v[230:233], v245 offset:4096
	ds_read_b128 v[234:237], v245 offset:6144
	s_waitcnt lgkmcnt(9)
	v_mfma_f32_16x16x32_bf16 v[32:35], v[206:209], v[136:139], v[32:35]
	v_mfma_f32_16x16x32_bf16 v[36:39], v[210:213], v[136:139], v[36:39]
	v_mfma_f32_16x16x32_bf16 v[40:43], v[214:217], v[136:139], v[40:43]
	v_mfma_f32_16x16x32_bf16 v[44:47], v[218:221], v[136:139], v[44:47]
	s_add_u32 m0, s42, 0x18000
	s_nop 0
	global_load_lds_dwordx4 v238, s[30:31]
	s_add_u32 m0, s42, 0x1a000
	s_nop 0
	global_load_lds_dwordx4 v239, s[30:31]
	ds_read_b128 v[160:163], v243
	ds_read_b128 v[164:167], v243 offset:2048
	s_waitcnt lgkmcnt(10)
	v_mfma_f32_16x16x32_bf16 v[48:51], v[206:209], v[140:143], v[48:51]
	v_mfma_f32_16x16x32_bf16 v[52:55], v[210:213], v[140:143], v[52:55]
	v_mfma_f32_16x16x32_bf16 v[56:59], v[214:217], v[140:143], v[56:59]
	v_mfma_f32_16x16x32_bf16 v[60:63], v[218:221], v[140:143], v[60:63]
	s_add_u32 m0, s42, 0x1c000
	s_nop 0
	global_load_lds_dwordx4 v240, s[30:31]
	s_add_u32 m0, s42, 0x1e000
	s_nop 0
	global_load_lds_dwordx4 v241, s[30:31]
	ds_read_b128 v[168:171], v243 offset:4096
	ds_read_b128 v[172:175], v243 offset:6144
	s_waitcnt lgkmcnt(11)
	v_mfma_f32_16x16x32_bf16 v[64:67], v[206:209], v[144:147], v[64:67]
	v_mfma_f32_16x16x32_bf16 v[68:71], v[210:213], v[144:147], v[68:71]
	v_mfma_f32_16x16x32_bf16 v[72:75], v[214:217], v[144:147], v[72:75]
	v_mfma_f32_16x16x32_bf16 v[76:79], v[218:221], v[144:147], v[76:79]
	ds_read_b128 v[176:179], v243 offset:8192
	ds_read_b128 v[180:183], v243 offset:10240
	s_waitcnt lgkmcnt(12)
	v_mfma_f32_16x16x32_bf16 v[80:83], v[206:209], v[148:151], v[80:83]
	v_mfma_f32_16x16x32_bf16 v[84:87], v[210:213], v[148:151], v[84:87]
	v_mfma_f32_16x16x32_bf16 v[88:91], v[214:217], v[148:151], v[88:91]
	v_mfma_f32_16x16x32_bf16 v[92:95], v[218:221], v[148:151], v[92:95]
	ds_read_b128 v[184:187], v243 offset:12288
	ds_read_b128 v[188:191], v243 offset:14336
	s_waitcnt lgkmcnt(13)
	v_mfma_f32_16x16x32_bf16 v[96:99], v[206:209], v[152:155], v[96:99]
	v_mfma_f32_16x16x32_bf16 v[100:103], v[210:213], v[152:155], v[100:103]
	v_mfma_f32_16x16x32_bf16 v[104:107], v[214:217], v[152:155], v[104:107]
	v_mfma_f32_16x16x32_bf16 v[108:111], v[218:221], v[152:155], v[108:111]
	s_waitcnt lgkmcnt(12)
	v_mfma_f32_16x16x32_bf16 v[112:115], v[206:209], v[156:159], v[112:115]
	v_mfma_f32_16x16x32_bf16 v[116:119], v[210:213], v[156:159], v[116:119]
	v_mfma_f32_16x16x32_bf16 v[120:123], v[214:217], v[156:159], v[120:123]
	v_mfma_f32_16x16x32_bf16 v[124:127], v[218:221], v[156:159], v[124:127]
	s_waitcnt lgkmcnt(7)
	v_mfma_f32_16x16x32_bf16 v[0:3], v[222:225], v[160:163], v[0:3]
	v_mfma_f32_16x16x32_bf16 v[4:7], v[226:229], v[160:163], v[4:7]
	v_mfma_f32_16x16x32_bf16 v[8:11], v[230:233], v[160:163], v[8:11]
	v_mfma_f32_16x16x32_bf16 v[12:15], v[234:237], v[160:163], v[12:15]
	s_waitcnt lgkmcnt(6)
	v_mfma_f32_16x16x32_bf16 v[16:19], v[222:225], v[164:167], v[16:19]
	v_mfma_f32_16x16x32_bf16 v[20:23], v[226:229], v[164:167], v[20:23]
	v_mfma_f32_16x16x32_bf16 v[24:27], v[230:233], v[164:167], v[24:27]
	v_mfma_f32_16x16x32_bf16 v[28:31], v[234:237], v[164:167], v[28:31]
	s_waitcnt lgkmcnt(5)
	v_mfma_f32_16x16x32_bf16 v[32:35], v[222:225], v[168:171], v[32:35]
	v_mfma_f32_16x16x32_bf16 v[36:39], v[226:229], v[168:171], v[36:39]
	v_mfma_f32_16x16x32_bf16 v[40:43], v[230:233], v[168:171], v[40:43]
	v_mfma_f32_16x16x32_bf16 v[44:47], v[234:237], v[168:171], v[44:47]
	s_waitcnt lgkmcnt(4)
	v_mfma_f32_16x16x32_bf16 v[48:51], v[222:225], v[172:175], v[48:51]
	v_mfma_f32_16x16x32_bf16 v[52:55], v[226:229], v[172:175], v[52:55]
	v_mfma_f32_16x16x32_bf16 v[56:59], v[230:233], v[172:175], v[56:59]
	v_mfma_f32_16x16x32_bf16 v[60:63], v[234:237], v[172:175], v[60:63]
	s_waitcnt lgkmcnt(3)
	v_mfma_f32_16x16x32_bf16 v[64:67], v[222:225], v[176:179], v[64:67]
	v_mfma_f32_16x16x32_bf16 v[68:71], v[226:229], v[176:179], v[68:71]
	v_mfma_f32_16x16x32_bf16 v[72:75], v[230:233], v[176:179], v[72:75]
	v_mfma_f32_16x16x32_bf16 v[76:79], v[234:237], v[176:179], v[76:79]
	s_waitcnt lgkmcnt(2)
	v_mfma_f32_16x16x32_bf16 v[80:83], v[222:225], v[180:183], v[80:83]
	v_mfma_f32_16x16x32_bf16 v[84:87], v[226:229], v[180:183], v[84:87]
	v_mfma_f32_16x16x32_bf16 v[88:91], v[230:233], v[180:183], v[88:91]
	v_mfma_f32_16x16x32_bf16 v[92:95], v[234:237], v[180:183], v[92:95]
	s_setprio 0
	s_waitcnt vmcnt(0) lgkmcnt(0)
	s_barrier
	s_add_u32 s28, s28, 0x80
	s_addc_u32 s29, s29, 0
	s_add_u32 s30, s30, 0x80
	s_addc_u32 s31, s31, 0
	s_cmp_eq_u32 s33, 7
	s_cselect_b32 s28, s22, s28
	s_cselect_b32 s29, s23, s29
	s_cselect_b32 s30, s24, s30
	s_cselect_b32 s31, s25, s31
	s_setprio 1
	ds_read_b128 v[206:209], v248
	ds_read_b128 v[210:213], v248 offset:2048
	ds_read_b128 v[214:217], v248 offset:4096
	ds_read_b128 v[218:221], v248 offset:6144
	ds_read_b128 v[128:131], v246
	ds_read_b128 v[132:135], v246 offset:2048
	ds_read_b128 v[136:139], v246 offset:4096
	ds_read_b128 v[140:143], v246 offset:6144
	ds_read_b128 v[144:147], v246 offset:8192
	ds_read_b128 v[148:151], v246 offset:10240
	ds_read_b128 v[152:155], v246 offset:12288
	ds_read_b128 v[156:159], v246 offset:14336
	v_mfma_f32_16x16x32_bf16 v[96:99], v[222:225], v[184:187], v[96:99]
	v_mfma_f32_16x16x32_bf16 v[100:103], v[226:229], v[184:187], v[100:103]
	v_mfma_f32_16x16x32_bf16 v[104:107], v[230:233], v[184:187], v[104:107]
	v_mfma_f32_16x16x32_bf16 v[108:111], v[234:237], v[184:187], v[108:111]
	v_mfma_f32_16x16x32_bf16 v[112:115], v[222:225], v[188:191], v[112:115]
	v_mfma_f32_16x16x32_bf16 v[116:119], v[226:229], v[188:191], v[116:119]
	v_mfma_f32_16x16x32_bf16 v[120:123], v[230:233], v[188:191], v[120:123]
	v_mfma_f32_16x16x32_bf16 v[124:127], v[234:237], v[188:191], v[124:127]
	s_waitcnt lgkmcnt(7)
	v_mfma_f32_16x16x32_bf16 v[0:3], v[206:209], v[128:131], v[0:3]
	v_mfma_f32_16x16x32_bf16 v[4:7], v[210:213], v[128:131], v[4:7]
	v_mfma_f32_16x16x32_bf16 v[8:11], v[214:217], v[128:131], v[8:11]
	v_mfma_f32_16x16x32_bf16 v[12:15], v[218:221], v[128:131], v[12:15]
	s_add_u32 m0, s42, 0x0
	s_nop 0
	global_load_lds_dwordx4 v238, s[28:29]
	s_add_u32 m0, s42, 0x2000
	s_nop 0
	global_load_lds_dwordx4 v239, s[28:29]
	ds_read_b128 v[222:225], v249
	ds_read_b128 v[226:229], v249 offset:2048
	s_waitcnt lgkmcnt(8)
	v_mfma_f32_16x16x32_bf16 v[16:19], v[206:209], v[132:135], v[16:19]
	v_mfma_f32_16x16x32_bf16 v[20:23], v[210:213], v[132:135], v[20:23]
	v_mfma_f32_16x16x32_bf16 v[24:27], v[214:217], v[132:135], v[24:27]
	v_mfma_f32_16x16x32_bf16 v[28:31], v[218:221], v[132:135], v[28:31]
	s_add_u32 m0, s42, 0x4000
	s_nop 0
	global_load_lds_dwordx4 v240, s[28:29]
	s_add_u32 m0, s42, 0x6000
	s_nop 0
	global_load_lds_dwordx4 v241, s[28:29]
	ds_read_b128 v[230:233], v249 offset:4096
	ds_read_b128 v[234:237], v249 offset:6144
	s_waitcnt lgkmcnt(9)
	v_mfma_f32_16x16x32_bf16 v[32:35], v[206:209], v[136:139], v[32:35]
	v_mfma_f32_16x16x32_bf16 v[36:39], v[210:213], v[136:139], v[36:39]
	v_mfma_f32_16x16x32_bf16 v[40:43], v[214:217], v[136:139], v[40:43]
	v_mfma_f32_16x16x32_bf16 v[44:47], v[218:221], v[136:139], v[44:47]
	s_add_u32 m0, s42, 0x8000
	s_nop 0
	global_load_lds_dwordx4 v238, s[30:31]
	s_add_u32 m0, s42, 0xa000
	s_nop 0
	global_load_lds_dwordx4 v239, s[30:31]
	ds_read_b128 v[160:163], v247
	ds_read_b128 v[164:167], v247 offset:2048
	s_waitcnt lgkmcnt(10)
	v_mfma_f32_16x16x32_bf16 v[48:51], v[206:209], v[140:143], v[48:51]
	v_mfma_f32_16x16x32_bf16 v[52:55], v[210:213], v[140:143], v[52:55]
	v_mfma_f32_16x16x32_bf16 v[56:59], v[214:217], v[140:143], v[56:59]
	v_mfma_f32_16x16x32_bf16 v[60:63], v[218:221], v[140:143], v[60:63]
	s_add_u32 m0, s42, 0xc000
	s_nop 0
	global_load_lds_dwordx4 v240, s[30:31]
	s_add_u32 m0, s42, 0xe000
	s_nop 0
	global_load_lds_dwordx4 v241, s[30:31]
	ds_read_b128 v[168:171], v247 offset:4096
	ds_read_b128 v[172:175], v247 offset:6144
	s_waitcnt lgkmcnt(11)
	v_mfma_f32_16x16x32_bf16 v[64:67], v[206:209], v[144:147], v[64:67]
	v_mfma_f32_16x16x32_bf16 v[68:71], v[210:213], v[144:147], v[68:71]
	v_mfma_f32_16x16x32_bf16 v[72:75], v[214:217], v[144:147], v[72:75]
	v_mfma_f32_16x16x32_bf16 v[76:79], v[218:221], v[144:147], v[76:79]
	ds_read_b128 v[176:179], v247 offset:8192
	ds_read_b128 v[180:183], v247 offset:10240
	s_waitcnt lgkmcnt(12)
	v_mfma_f32_16x16x32_bf16 v[80:83], v[206:209], v[148:151], v[80:83]
	v_mfma_f32_16x16x32_bf16 v[84:87], v[210:213], v[148:151], v[84:87]
	v_mfma_f32_16x16x32_bf16 v[88:91], v[214:217], v[148:151], v[88:91]
	v_mfma_f32_16x16x32_bf16 v[92:95], v[218:221], v[148:151], v[92:95]
	ds_read_b128 v[184:187], v247 offset:12288
	ds_read_b128 v[188:191], v247 offset:14336
	s_waitcnt lgkmcnt(13)
	v_mfma_f32_16x16x32_bf16 v[96:99], v[206:209], v[152:155], v[96:99]
	v_mfma_f32_16x16x32_bf16 v[100:103], v[210:213], v[152:155], v[100:103]
	v_mfma_f32_16x16x32_bf16 v[104:107], v[214:217], v[152:155], v[104:107]
	v_mfma_f32_16x16x32_bf16 v[108:111], v[218:221], v[152:155], v[108:111]
	s_waitcnt lgkmcnt(12)
	v_mfma_f32_16x16x32_bf16 v[112:115], v[206:209], v[156:159], v[112:115]
	v_mfma_f32_16x16x32_bf16 v[116:119], v[210:213], v[156:159], v[116:119]
	v_mfma_f32_16x16x32_bf16 v[120:123], v[214:217], v[156:159], v[120:123]
	v_mfma_f32_16x16x32_bf16 v[124:127], v[218:221], v[156:159], v[124:127]
	s_waitcnt lgkmcnt(7)
	v_mfma_f32_16x16x32_bf16 v[0:3], v[222:225], v[160:163], v[0:3]
	v_mfma_f32_16x16x32_bf16 v[4:7], v[226:229], v[160:163], v[4:7]
	v_mfma_f32_16x16x32_bf16 v[8:11], v[230:233], v[160:163], v[8:11]
	v_mfma_f32_16x16x32_bf16 v[12:15], v[234:237], v[160:163], v[12:15]
	s_waitcnt lgkmcnt(6)
	v_mfma_f32_16x16x32_bf16 v[16:19], v[222:225], v[164:167], v[16:19]
	v_mfma_f32_16x16x32_bf16 v[20:23], v[226:229], v[164:167], v[20:23]
	v_mfma_f32_16x16x32_bf16 v[24:27], v[230:233], v[164:167], v[24:27]
	v_mfma_f32_16x16x32_bf16 v[28:31], v[234:237], v[164:167], v[28:31]
	s_waitcnt lgkmcnt(5)
	v_mfma_f32_16x16x32_bf16 v[32:35], v[222:225], v[168:171], v[32:35]
	v_mfma_f32_16x16x32_bf16 v[36:39], v[226:229], v[168:171], v[36:39]
	v_mfma_f32_16x16x32_bf16 v[40:43], v[230:233], v[168:171], v[40:43]
	v_mfma_f32_16x16x32_bf16 v[44:47], v[234:237], v[168:171], v[44:47]
	s_waitcnt lgkmcnt(4)
	v_mfma_f32_16x16x32_bf16 v[48:51], v[222:225], v[172:175], v[48:51]
	v_mfma_f32_16x16x32_bf16 v[52:55], v[226:229], v[172:175], v[52:55]
	v_mfma_f32_16x16x32_bf16 v[56:59], v[230:233], v[172:175], v[56:59]
	v_mfma_f32_16x16x32_bf16 v[60:63], v[234:237], v[172:175], v[60:63]
	s_waitcnt lgkmcnt(3)
	v_mfma_f32_16x16x32_bf16 v[64:67], v[222:225], v[176:179], v[64:67]
	v_mfma_f32_16x16x32_bf16 v[68:71], v[226:229], v[176:179], v[68:71]
	v_mfma_f32_16x16x32_bf16 v[72:75], v[230:233], v[176:179], v[72:75]
	v_mfma_f32_16x16x32_bf16 v[76:79], v[234:237], v[176:179], v[76:79]
	s_waitcnt lgkmcnt(2)
	v_mfma_f32_16x16x32_bf16 v[80:83], v[222:225], v[180:183], v[80:83]
	v_mfma_f32_16x16x32_bf16 v[84:87], v[226:229], v[180:183], v[84:87]
	v_mfma_f32_16x16x32_bf16 v[88:91], v[230:233], v[180:183], v[88:91]
	v_mfma_f32_16x16x32_bf16 v[92:95], v[234:237], v[180:183], v[92:95]
	s_setprio 0
	s_waitcnt lgkmcnt(0)
	s_add_u32 s28, s28, 0x80
	s_addc_u32 s29, s29, 0
	s_add_u32 s30, s30, 0x80
	s_addc_u32 s31, s31, 0
	s_add_i32 s33, s33, 1
	s_cmp_lt_u32 s33, 8
	s_cbranch_scc1 .Lgl_ktop_ffnup0
	v_mfma_f32_16x16x32_bf16 v[96:99], v[222:225], v[184:187], v[96:99]
	v_mfma_f32_16x16x32_bf16 v[100:103], v[226:229], v[184:187], v[100:103]
	v_mfma_f32_16x16x32_bf16 v[104:107], v[230:233], v[184:187], v[104:107]
	v_mfma_f32_16x16x32_bf16 v[108:111], v[234:237], v[184:187], v[108:111]
	v_mfma_f32_16x16x32_bf16 v[112:115], v[222:225], v[188:191], v[112:115]
	v_mfma_f32_16x16x32_bf16 v[116:119], v[226:229], v[188:191], v[116:119]
	v_mfma_f32_16x16x32_bf16 v[120:123], v[230:233], v[188:191], v[120:123]
	v_mfma_f32_16x16x32_bf16 v[124:127], v[234:237], v[188:191], v[124:127]
	s_mul_i32 s98, s14, 0x1600
	s_add_u32 s98, s98, s15
	s_add_u32 s98, s98, 0x28c4000
	s_add_u32 s100, s34, s98
	s_addc_u32 s101, s35, 0
	v_and_b32_e32 v168, 15, v204
	v_lshrrev_b32_e32 v169, 8, v204
	v_lshl_add_u32 v168, v169, 7, v168
	v_mul_u32_u24_e32 v168, 0x1600, v168
	v_and_b32_e32 v169, 0xc0, v204
	v_add_u32_e32 v168, v168, v169
	v_bfe_u32 v169, v204, 4, 1
	v_lshl_add_u32 v168, v169, 5, v168
	v_bfe_u32 v169, v204, 5, 1
	v_lshl_add_u32 v168, v169, 4, v168
	s_nop 7
	s_nop 7
	v_mul_f32_e32 v160, 0xbfb8aa3b, v0
	v_mul_f32_e32 v161, 0xbfb8aa3b, v1
	v_mul_f32_e32 v162, 0xbfb8aa3b, v2
	v_mul_f32_e32 v163, 0xbfb8aa3b, v3
	v_mul_f32_e32 v164, 0xbfb8aa3b, v8
	v_mul_f32_e32 v165, 0xbfb8aa3b, v9
	v_mul_f32_e32 v166, 0xbfb8aa3b, v10
	v_mul_f32_e32 v167, 0xbfb8aa3b, v11
	v_exp_f32_e32 v160, v160
	v_exp_f32_e32 v161, v161
	v_exp_f32_e32 v162, v162
	v_exp_f32_e32 v163, v163
	v_exp_f32_e32 v164, v164
	v_exp_f32_e32 v165, v165
	v_exp_f32_e32 v166, v166
	v_exp_f32_e32 v167, v167
	v_add_f32_e32 v160, 1.0, v160
	v_add_f32_e32 v161, 1.0, v161
	v_add_f32_e32 v162, 1.0, v162
	v_add_f32_e32 v163, 1.0, v163
	v_add_f32_e32 v164, 1.0, v164
	v_add_f32_e32 v165, 1.0, v165
	v_add_f32_e32 v166, 1.0, v166
	v_add_f32_e32 v167, 1.0, v167
	v_rcp_f32_e32 v160, v160
	v_rcp_f32_e32 v161, v161
	v_rcp_f32_e32 v162, v162
	v_rcp_f32_e32 v163, v163
	v_rcp_f32_e32 v164, v164
	v_rcp_f32_e32 v165, v165
	v_rcp_f32_e32 v166, v166
	v_rcp_f32_e32 v167, v167
	v_mul_f32_e32 v0, v0, v160
	v_mul_f32_e32 v1, v1, v161
	v_mul_f32_e32 v2, v2, v162
	v_mul_f32_e32 v3, v3, v163
	v_mul_f32_e32 v8, v8, v164
	v_mul_f32_e32 v9, v9, v165
	v_mul_f32_e32 v10, v10, v166
	v_mul_f32_e32 v11, v11, v167
	v_mul_f32_e32 v4, v0, v4
	v_mul_f32_e32 v5, v1, v5
	v_mul_f32_e32 v6, v2, v6
	v_mul_f32_e32 v7, v3, v7
	v_mul_f32_e32 v12, v8, v12
	v_mul_f32_e32 v13, v9, v13
	v_mul_f32_e32 v14, v10, v14
	v_mul_f32_e32 v15, v11, v15
	v_cvt_pk_bf16_f32 v0, v4, v5
	v_cvt_pk_bf16_f32 v1, v6, v7
	v_cvt_pk_bf16_f32 v2, v12, v13
	v_cvt_pk_bf16_f32 v3, v14, v15
	s_nop 1
	v_permlane16_swap_b32_e32 v0, v2
	v_permlane16_swap_b32_e32 v1, v3
	global_store_dwordx4 v168, v[0:3], s[100:101] sc1
	s_add_u32 s100, s100, 0x16000
	s_addc_u32 s101, s101, 0
	v_mul_f32_e32 v160, 0xbfb8aa3b, v16
	v_mul_f32_e32 v161, 0xbfb8aa3b, v17
	v_mul_f32_e32 v162, 0xbfb8aa3b, v18
	v_mul_f32_e32 v163, 0xbfb8aa3b, v19
	v_mul_f32_e32 v164, 0xbfb8aa3b, v24
	v_mul_f32_e32 v165, 0xbfb8aa3b, v25
	v_mul_f32_e32 v166, 0xbfb8aa3b, v26
	v_mul_f32_e32 v167, 0xbfb8aa3b, v27
	v_exp_f32_e32 v160, v160
	v_exp_f32_e32 v161, v161
	v_exp_f32_e32 v162, v162
	v_exp_f32_e32 v163, v163
	v_exp_f32_e32 v164, v164
	v_exp_f32_e32 v165, v165
	v_exp_f32_e32 v166, v166
	v_exp_f32_e32 v167, v167
	v_add_f32_e32 v160, 1.0, v160
	v_add_f32_e32 v161, 1.0, v161
	v_add_f32_e32 v162, 1.0, v162
	v_add_f32_e32 v163, 1.0, v163
	v_add_f32_e32 v164, 1.0, v164
	v_add_f32_e32 v165, 1.0, v165
	v_add_f32_e32 v166, 1.0, v166
	v_add_f32_e32 v167, 1.0, v167
	v_rcp_f32_e32 v160, v160
	v_rcp_f32_e32 v161, v161
	v_rcp_f32_e32 v162, v162
	v_rcp_f32_e32 v163, v163
	v_rcp_f32_e32 v164, v164
	v_rcp_f32_e32 v165, v165
	v_rcp_f32_e32 v166, v166
	v_rcp_f32_e32 v167, v167
	v_mul_f32_e32 v16, v16, v160
	v_mul_f32_e32 v17, v17, v161
	v_mul_f32_e32 v18, v18, v162
	v_mul_f32_e32 v19, v19, v163
	v_mul_f32_e32 v24, v24, v164
	v_mul_f32_e32 v25, v25, v165
	v_mul_f32_e32 v26, v26, v166
	v_mul_f32_e32 v27, v27, v167
	v_mul_f32_e32 v20, v16, v20
	v_mul_f32_e32 v21, v17, v21
	v_mul_f32_e32 v22, v18, v22
	v_mul_f32_e32 v23, v19, v23
	v_mul_f32_e32 v28, v24, v28
	v_mul_f32_e32 v29, v25, v29
	v_mul_f32_e32 v30, v26, v30
	v_mul_f32_e32 v31, v27, v31
	v_cvt_pk_bf16_f32 v16, v20, v21
	v_cvt_pk_bf16_f32 v17, v22, v23
	v_cvt_pk_bf16_f32 v18, v28, v29
	v_cvt_pk_bf16_f32 v19, v30, v31
	s_nop 1
	v_permlane16_swap_b32_e32 v16, v18
	v_permlane16_swap_b32_e32 v17, v19
	global_store_dwordx4 v168, v[16:19], s[100:101] sc1
	s_add_u32 s100, s100, 0x16000
	s_addc_u32 s101, s101, 0
	v_mul_f32_e32 v160, 0xbfb8aa3b, v32
	v_mul_f32_e32 v161, 0xbfb8aa3b, v33
	v_mul_f32_e32 v162, 0xbfb8aa3b, v34
	v_mul_f32_e32 v163, 0xbfb8aa3b, v35
	v_mul_f32_e32 v164, 0xbfb8aa3b, v40
	v_mul_f32_e32 v165, 0xbfb8aa3b, v41
	v_mul_f32_e32 v166, 0xbfb8aa3b, v42
	v_mul_f32_e32 v167, 0xbfb8aa3b, v43
	v_exp_f32_e32 v160, v160
	v_exp_f32_e32 v161, v161
	v_exp_f32_e32 v162, v162
	v_exp_f32_e32 v163, v163
	v_exp_f32_e32 v164, v164
	v_exp_f32_e32 v165, v165
	v_exp_f32_e32 v166, v166
	v_exp_f32_e32 v167, v167
	v_add_f32_e32 v160, 1.0, v160
	v_add_f32_e32 v161, 1.0, v161
	v_add_f32_e32 v162, 1.0, v162
	v_add_f32_e32 v163, 1.0, v163
	v_add_f32_e32 v164, 1.0, v164
	v_add_f32_e32 v165, 1.0, v165
	v_add_f32_e32 v166, 1.0, v166
	v_add_f32_e32 v167, 1.0, v167
	v_rcp_f32_e32 v160, v160
	v_rcp_f32_e32 v161, v161
	v_rcp_f32_e32 v162, v162
	v_rcp_f32_e32 v163, v163
	v_rcp_f32_e32 v164, v164
	v_rcp_f32_e32 v165, v165
	v_rcp_f32_e32 v166, v166
	v_rcp_f32_e32 v167, v167
	v_mul_f32_e32 v32, v32, v160
	v_mul_f32_e32 v33, v33, v161
	v_mul_f32_e32 v34, v34, v162
	v_mul_f32_e32 v35, v35, v163
	v_mul_f32_e32 v40, v40, v164
	v_mul_f32_e32 v41, v41, v165
	v_mul_f32_e32 v42, v42, v166
	v_mul_f32_e32 v43, v43, v167
	v_mul_f32_e32 v36, v32, v36
	v_mul_f32_e32 v37, v33, v37
	v_mul_f32_e32 v38, v34, v38
	v_mul_f32_e32 v39, v35, v39
	v_mul_f32_e32 v44, v40, v44
	v_mul_f32_e32 v45, v41, v45
	v_mul_f32_e32 v46, v42, v46
	v_mul_f32_e32 v47, v43, v47
	v_cvt_pk_bf16_f32 v32, v36, v37
	v_cvt_pk_bf16_f32 v33, v38, v39
	v_cvt_pk_bf16_f32 v34, v44, v45
	v_cvt_pk_bf16_f32 v35, v46, v47
	s_nop 1
	v_permlane16_swap_b32_e32 v32, v34
	v_permlane16_swap_b32_e32 v33, v35
	global_store_dwordx4 v168, v[32:35], s[100:101] sc1
	s_add_u32 s100, s100, 0x16000
	s_addc_u32 s101, s101, 0
	v_mul_f32_e32 v160, 0xbfb8aa3b, v48
	v_mul_f32_e32 v161, 0xbfb8aa3b, v49
	v_mul_f32_e32 v162, 0xbfb8aa3b, v50
	v_mul_f32_e32 v163, 0xbfb8aa3b, v51
	v_mul_f32_e32 v164, 0xbfb8aa3b, v56
	v_mul_f32_e32 v165, 0xbfb8aa3b, v57
	v_mul_f32_e32 v166, 0xbfb8aa3b, v58
	v_mul_f32_e32 v167, 0xbfb8aa3b, v59
	v_exp_f32_e32 v160, v160
	v_exp_f32_e32 v161, v161
	v_exp_f32_e32 v162, v162
	v_exp_f32_e32 v163, v163
	v_exp_f32_e32 v164, v164
	v_exp_f32_e32 v165, v165
	v_exp_f32_e32 v166, v166
	v_exp_f32_e32 v167, v167
	v_add_f32_e32 v160, 1.0, v160
	v_add_f32_e32 v161, 1.0, v161
	v_add_f32_e32 v162, 1.0, v162
	v_add_f32_e32 v163, 1.0, v163
	v_add_f32_e32 v164, 1.0, v164
	v_add_f32_e32 v165, 1.0, v165
	v_add_f32_e32 v166, 1.0, v166
	v_add_f32_e32 v167, 1.0, v167
	v_rcp_f32_e32 v160, v160
	v_rcp_f32_e32 v161, v161
	v_rcp_f32_e32 v162, v162
	v_rcp_f32_e32 v163, v163
	v_rcp_f32_e32 v164, v164
	v_rcp_f32_e32 v165, v165
	v_rcp_f32_e32 v166, v166
	v_rcp_f32_e32 v167, v167
	v_mul_f32_e32 v48, v48, v160
	v_mul_f32_e32 v49, v49, v161
	v_mul_f32_e32 v50, v50, v162
	v_mul_f32_e32 v51, v51, v163
	v_mul_f32_e32 v56, v56, v164
	v_mul_f32_e32 v57, v57, v165
	v_mul_f32_e32 v58, v58, v166
	v_mul_f32_e32 v59, v59, v167
	v_mul_f32_e32 v52, v48, v52
	v_mul_f32_e32 v53, v49, v53
	v_mul_f32_e32 v54, v50, v54
	v_mul_f32_e32 v55, v51, v55
	v_mul_f32_e32 v60, v56, v60
	v_mul_f32_e32 v61, v57, v61
	v_mul_f32_e32 v62, v58, v62
	v_mul_f32_e32 v63, v59, v63
	v_cvt_pk_bf16_f32 v48, v52, v53
	v_cvt_pk_bf16_f32 v49, v54, v55
	v_cvt_pk_bf16_f32 v50, v60, v61
	v_cvt_pk_bf16_f32 v51, v62, v63
	s_nop 1
	v_permlane16_swap_b32_e32 v48, v50
	v_permlane16_swap_b32_e32 v49, v51
	global_store_dwordx4 v168, v[48:51], s[100:101] sc1
	s_add_u32 s100, s100, 0x16000
	s_addc_u32 s101, s101, 0
	v_mul_f32_e32 v160, 0xbfb8aa3b, v64
	v_mul_f32_e32 v161, 0xbfb8aa3b, v65
	v_mul_f32_e32 v162, 0xbfb8aa3b, v66
	v_mul_f32_e32 v163, 0xbfb8aa3b, v67
	v_mul_f32_e32 v164, 0xbfb8aa3b, v72
	v_mul_f32_e32 v165, 0xbfb8aa3b, v73
	v_mul_f32_e32 v166, 0xbfb8aa3b, v74
	v_mul_f32_e32 v167, 0xbfb8aa3b, v75
	v_exp_f32_e32 v160, v160
	v_exp_f32_e32 v161, v161
	v_exp_f32_e32 v162, v162
	v_exp_f32_e32 v163, v163
	v_exp_f32_e32 v164, v164
	v_exp_f32_e32 v165, v165
	v_exp_f32_e32 v166, v166
	v_exp_f32_e32 v167, v167
	v_add_f32_e32 v160, 1.0, v160
	v_add_f32_e32 v161, 1.0, v161
	v_add_f32_e32 v162, 1.0, v162
	v_add_f32_e32 v163, 1.0, v163
	v_add_f32_e32 v164, 1.0, v164
	v_add_f32_e32 v165, 1.0, v165
	v_add_f32_e32 v166, 1.0, v166
	v_add_f32_e32 v167, 1.0, v167
	v_rcp_f32_e32 v160, v160
	v_rcp_f32_e32 v161, v161
	v_rcp_f32_e32 v162, v162
	v_rcp_f32_e32 v163, v163
	v_rcp_f32_e32 v164, v164
	v_rcp_f32_e32 v165, v165
	v_rcp_f32_e32 v166, v166
	v_rcp_f32_e32 v167, v167
	v_mul_f32_e32 v64, v64, v160
	v_mul_f32_e32 v65, v65, v161
	v_mul_f32_e32 v66, v66, v162
	v_mul_f32_e32 v67, v67, v163
	v_mul_f32_e32 v72, v72, v164
	v_mul_f32_e32 v73, v73, v165
	v_mul_f32_e32 v74, v74, v166
	v_mul_f32_e32 v75, v75, v167
	v_mul_f32_e32 v68, v64, v68
	v_mul_f32_e32 v69, v65, v69
	v_mul_f32_e32 v70, v66, v70
	v_mul_f32_e32 v71, v67, v71
	v_mul_f32_e32 v76, v72, v76
	v_mul_f32_e32 v77, v73, v77
	v_mul_f32_e32 v78, v74, v78
	v_mul_f32_e32 v79, v75, v79
	v_cvt_pk_bf16_f32 v64, v68, v69
	v_cvt_pk_bf16_f32 v65, v70, v71
	v_cvt_pk_bf16_f32 v66, v76, v77
	v_cvt_pk_bf16_f32 v67, v78, v79
	s_nop 1
	v_permlane16_swap_b32_e32 v64, v66
	v_permlane16_swap_b32_e32 v65, v67
	global_store_dwordx4 v168, v[64:67], s[100:101] sc1
	s_add_u32 s100, s100, 0x16000
	s_addc_u32 s101, s101, 0
	v_mul_f32_e32 v160, 0xbfb8aa3b, v80
	v_mul_f32_e32 v161, 0xbfb8aa3b, v81
	v_mul_f32_e32 v162, 0xbfb8aa3b, v82
	v_mul_f32_e32 v163, 0xbfb8aa3b, v83
	v_mul_f32_e32 v164, 0xbfb8aa3b, v88
	v_mul_f32_e32 v165, 0xbfb8aa3b, v89
	v_mul_f32_e32 v166, 0xbfb8aa3b, v90
	v_mul_f32_e32 v167, 0xbfb8aa3b, v91
	v_exp_f32_e32 v160, v160
	v_exp_f32_e32 v161, v161
	v_exp_f32_e32 v162, v162
	v_exp_f32_e32 v163, v163
	v_exp_f32_e32 v164, v164
	v_exp_f32_e32 v165, v165
	v_exp_f32_e32 v166, v166
	v_exp_f32_e32 v167, v167
	v_add_f32_e32 v160, 1.0, v160
	v_add_f32_e32 v161, 1.0, v161
	v_add_f32_e32 v162, 1.0, v162
	v_add_f32_e32 v163, 1.0, v163
	v_add_f32_e32 v164, 1.0, v164
	v_add_f32_e32 v165, 1.0, v165
	v_add_f32_e32 v166, 1.0, v166
	v_add_f32_e32 v167, 1.0, v167
	v_rcp_f32_e32 v160, v160
	v_rcp_f32_e32 v161, v161
	v_rcp_f32_e32 v162, v162
	v_rcp_f32_e32 v163, v163
	v_rcp_f32_e32 v164, v164
	v_rcp_f32_e32 v165, v165
	v_rcp_f32_e32 v166, v166
	v_rcp_f32_e32 v167, v167
	v_mul_f32_e32 v80, v80, v160
	v_mul_f32_e32 v81, v81, v161
	v_mul_f32_e32 v82, v82, v162
	v_mul_f32_e32 v83, v83, v163
	v_mul_f32_e32 v88, v88, v164
	v_mul_f32_e32 v89, v89, v165
	v_mul_f32_e32 v90, v90, v166
	v_mul_f32_e32 v91, v91, v167
	v_mul_f32_e32 v84, v80, v84
	v_mul_f32_e32 v85, v81, v85
	v_mul_f32_e32 v86, v82, v86
	v_mul_f32_e32 v87, v83, v87
	v_mul_f32_e32 v92, v88, v92
	v_mul_f32_e32 v93, v89, v93
	v_mul_f32_e32 v94, v90, v94
	v_mul_f32_e32 v95, v91, v95
	v_cvt_pk_bf16_f32 v80, v84, v85
	v_cvt_pk_bf16_f32 v81, v86, v87
	v_cvt_pk_bf16_f32 v82, v92, v93
	v_cvt_pk_bf16_f32 v83, v94, v95
	s_nop 1
	v_permlane16_swap_b32_e32 v80, v82
	v_permlane16_swap_b32_e32 v81, v83
	global_store_dwordx4 v168, v[80:83], s[100:101] sc1
	s_add_u32 s100, s100, 0x16000
	s_addc_u32 s101, s101, 0
	v_mul_f32_e32 v160, 0xbfb8aa3b, v96
	v_mul_f32_e32 v161, 0xbfb8aa3b, v97
	v_mul_f32_e32 v162, 0xbfb8aa3b, v98
	v_mul_f32_e32 v163, 0xbfb8aa3b, v99
	v_mul_f32_e32 v164, 0xbfb8aa3b, v104
	v_mul_f32_e32 v165, 0xbfb8aa3b, v105
	v_mul_f32_e32 v166, 0xbfb8aa3b, v106
	v_mul_f32_e32 v167, 0xbfb8aa3b, v107
	v_exp_f32_e32 v160, v160
	v_exp_f32_e32 v161, v161
	v_exp_f32_e32 v162, v162
	v_exp_f32_e32 v163, v163
	v_exp_f32_e32 v164, v164
	v_exp_f32_e32 v165, v165
	v_exp_f32_e32 v166, v166
	v_exp_f32_e32 v167, v167
	v_add_f32_e32 v160, 1.0, v160
	v_add_f32_e32 v161, 1.0, v161
	v_add_f32_e32 v162, 1.0, v162
	v_add_f32_e32 v163, 1.0, v163
	v_add_f32_e32 v164, 1.0, v164
	v_add_f32_e32 v165, 1.0, v165
	v_add_f32_e32 v166, 1.0, v166
	v_add_f32_e32 v167, 1.0, v167
	v_rcp_f32_e32 v160, v160
	v_rcp_f32_e32 v161, v161
	v_rcp_f32_e32 v162, v162
	v_rcp_f32_e32 v163, v163
	v_rcp_f32_e32 v164, v164
	v_rcp_f32_e32 v165, v165
	v_rcp_f32_e32 v166, v166
	v_rcp_f32_e32 v167, v167
	v_mul_f32_e32 v96, v96, v160
	v_mul_f32_e32 v97, v97, v161
	v_mul_f32_e32 v98, v98, v162
	v_mul_f32_e32 v99, v99, v163
	v_mul_f32_e32 v104, v104, v164
	v_mul_f32_e32 v105, v105, v165
	v_mul_f32_e32 v106, v106, v166
	v_mul_f32_e32 v107, v107, v167
	v_mul_f32_e32 v100, v96, v100
	v_mul_f32_e32 v101, v97, v101
	v_mul_f32_e32 v102, v98, v102
	v_mul_f32_e32 v103, v99, v103
	v_mul_f32_e32 v108, v104, v108
	v_mul_f32_e32 v109, v105, v109
	v_mul_f32_e32 v110, v106, v110
	v_mul_f32_e32 v111, v107, v111
	v_cvt_pk_bf16_f32 v96, v100, v101
	v_cvt_pk_bf16_f32 v97, v102, v103
	v_cvt_pk_bf16_f32 v98, v108, v109
	v_cvt_pk_bf16_f32 v99, v110, v111
	s_nop 1
	v_permlane16_swap_b32_e32 v96, v98
	v_permlane16_swap_b32_e32 v97, v99
	global_store_dwordx4 v168, v[96:99], s[100:101] sc1
	s_add_u32 s100, s100, 0x16000
	s_addc_u32 s101, s101, 0
	v_mul_f32_e32 v160, 0xbfb8aa3b, v112
	v_mul_f32_e32 v161, 0xbfb8aa3b, v113
	v_mul_f32_e32 v162, 0xbfb8aa3b, v114
	v_mul_f32_e32 v163, 0xbfb8aa3b, v115
	v_mul_f32_e32 v164, 0xbfb8aa3b, v120
	v_mul_f32_e32 v165, 0xbfb8aa3b, v121
	v_mul_f32_e32 v166, 0xbfb8aa3b, v122
	v_mul_f32_e32 v167, 0xbfb8aa3b, v123
	v_exp_f32_e32 v160, v160
	v_exp_f32_e32 v161, v161
	v_exp_f32_e32 v162, v162
	v_exp_f32_e32 v163, v163
	v_exp_f32_e32 v164, v164
	v_exp_f32_e32 v165, v165
	v_exp_f32_e32 v166, v166
	v_exp_f32_e32 v167, v167
	v_add_f32_e32 v160, 1.0, v160
	v_add_f32_e32 v161, 1.0, v161
	v_add_f32_e32 v162, 1.0, v162
	v_add_f32_e32 v163, 1.0, v163
	v_add_f32_e32 v164, 1.0, v164
	v_add_f32_e32 v165, 1.0, v165
	v_add_f32_e32 v166, 1.0, v166
	v_add_f32_e32 v167, 1.0, v167
	v_rcp_f32_e32 v160, v160
	v_rcp_f32_e32 v161, v161
	v_rcp_f32_e32 v162, v162
	v_rcp_f32_e32 v163, v163
	v_rcp_f32_e32 v164, v164
	v_rcp_f32_e32 v165, v165
	v_rcp_f32_e32 v166, v166
	v_rcp_f32_e32 v167, v167
	v_mul_f32_e32 v112, v112, v160
	v_mul_f32_e32 v113, v113, v161
	v_mul_f32_e32 v114, v114, v162
	v_mul_f32_e32 v115, v115, v163
	v_mul_f32_e32 v120, v120, v164
	v_mul_f32_e32 v121, v121, v165
	v_mul_f32_e32 v122, v122, v166
	v_mul_f32_e32 v123, v123, v167
	v_mul_f32_e32 v116, v112, v116
	v_mul_f32_e32 v117, v113, v117
	v_mul_f32_e32 v118, v114, v118
	v_mul_f32_e32 v119, v115, v119
	v_mul_f32_e32 v124, v120, v124
	v_mul_f32_e32 v125, v121, v125
	v_mul_f32_e32 v126, v122, v126
	v_mul_f32_e32 v127, v123, v127
	v_cvt_pk_bf16_f32 v112, v116, v117
	v_cvt_pk_bf16_f32 v113, v118, v119
	v_cvt_pk_bf16_f32 v114, v124, v125
	v_cvt_pk_bf16_f32 v115, v126, v127
	s_nop 1
	v_permlane16_swap_b32_e32 v112, v114
	v_permlane16_swap_b32_e32 v113, v115
	global_store_dwordx4 v168, v[112:115], s[100:101] sc1
	s_and_b64 vcc, exec, s[26:27]
	s_mov_b32 s14, s20
	s_mov_b32 s15, s21
	s_mov_b64 s[10:11], s[22:23]
	s_mov_b64 s[12:13], s[24:25]
	s_mov_b32 s8, s43
	s_cbranch_vccz .Lgl_tile_ffnup0
	s_waitcnt vmcnt(0)
	s_barrier

.LBB0_1443:
	s_cmp_lt_i32 s88, 16
	s_cselect_b64 s[6:7], -1, 0
	s_and_b64 s[4:5], s[6:7], s[4:5]
	s_andn2_b64 vcc, exec, s[4:5]
	s_cbranch_vccnz .LBB0_1451
	s_cmpk_gt_i32 s2, 0x2bf
	s_cbranch_scc1 .LBB0_1451
	s_load_dword s9, s[0:1], 0x120
	v_readfirstlane_b32 s42, v205
	v_and_b32_e32 v192, 15, v204
	v_bfe_u32 v193, v204, 4, 2
	v_lshrrev_b32_e32 v194, 8, v204
	v_bfe_u32 v195, v204, 6, 2
	v_bfe_u32 v196, v204, 1, 3
	v_xor_b32_e32 v197, v193, v196
	v_xor_b32_e32 v198, 4, v197
	v_lshlrev_b32_e32 v197, 4, v197
	v_lshlrev_b32_e32 v198, 4, v198
	v_lshlrev_b32_e32 v199, 14, v194
	v_lshl_add_u32 v199, v192, 7, v199
	v_add_u32_e32 v242, v199, v197
	v_add_u32_e32 v243, v199, v198
	v_lshlrev_b32_e32 v199, 13, v195
	v_lshl_add_u32 v199, v192, 7, v199
	v_add_u32_e32 v199, 0x8000, v199
	v_add_u32_e32 v244, v199, v197
	v_add_u32_e32 v245, v199, v198
	v_add_u32_e32 v246, 0x10000, v242
	v_add_u32_e32 v248, 0x10000, v244
	v_add_u32_e32 v247, 0x10000, v243
	v_add_u32_e32 v249, 0x10000, v245
	v_lshrrev_b32_e32 v199, 3, v204
	v_and_b32_e32 v200, 7, v204
	v_bfe_u32 v201, v204, 4, 3
	v_xor_b32_e32 v200, v200, v201
	v_lshlrev_b32_e32 v200, 4, v200
	v_lshl_add_u32 v238, v199, 11, v200
	v_add_u32_e32 v239, 0x20000, v238
	v_add_u32_e32 v240, 0x40000, v238
	v_add_u32_e32 v241, 0x60000, v238
	s_lshl_b32 s42, s42, 10
	s_mov_b32 s8, s2
	s_and_b32 s44, s8, 7
	s_mulk_i32 s44, 0x58
	s_lshr_b32 s45, s8, 3
	s_add_i32 s44, s44, s45
	s_cmpk_ge_i32 s44, 176
	s_cselect_b32 s45, 1, 0
	s_cmpk_ge_i32 s44, 352
	s_cselect_b32 s98, 1, 0
	s_add_i32 s45, s45, s98
	s_cmpk_ge_i32 s44, 528
	s_cselect_b32 s98, 1, 0
	s_add_i32 s45, s45, s98
	s_mul_i32 s98, s45, 176
	s_sub_i32 s44, s44, s98
	s_and_b32 s98, s44, 7
	s_lshl_b32 s45, s45, 3
	s_add_i32 s45, s45, s98
	s_lshl_b32 s14, s45, 8
	s_lshr_b32 s44, s44, 3
	s_lshl_b32 s15, s44, 8
	s_mul_i32 s44, s14, 0x800
	s_add_u32 s44, s44, 0x8a44000
	s_add_u32 s10, s34, s44
	s_addc_u32 s11, s35, 0
	s_mul_i32 s44, s15, 0x800
	s_add_u32 s44, s44, 0x12a0000
	s_add_u32 s12, s34, s44
	s_addc_u32 s13, s35, 0
	s_waitcnt vmcnt(0) lgkmcnt(0)
	s_barrier
	s_add_u32 m0, s42, 0x0
	s_nop 0
	global_load_lds_dwordx4 v238, s[10:11]
	s_add_u32 m0, s42, 0x2000
	s_nop 0
	global_load_lds_dwordx4 v239, s[10:11]
	s_add_u32 m0, s42, 0x4000
	s_nop 0
	global_load_lds_dwordx4 v240, s[10:11]
	s_add_u32 m0, s42, 0x6000
	s_nop 0
	global_load_lds_dwordx4 v241, s[10:11]
	s_add_u32 m0, s42, 0x8000
	s_nop 0
	global_load_lds_dwordx4 v238, s[12:13]
	s_add_u32 m0, s42, 0xa000
	s_nop 0
	global_load_lds_dwordx4 v239, s[12:13]
	s_add_u32 m0, s42, 0xc000
	s_nop 0
	global_load_lds_dwordx4 v240, s[12:13]
	s_add_u32 m0, s42, 0xe000
	s_nop 0
	global_load_lds_dwordx4 v241, s[12:13]
	s_waitcnt vmcnt(0)
.Lgl_tile_ffnup1:
	s_add_i32 s43, s8, s9
	s_cmpk_lt_i32 s43, 704
	s_cselect_b64 s[26:27], 0, -1
	s_cbranch_scc0 .Lgl_nonext_ffnup1
	s_and_b32 s44, s43, 7
	s_mulk_i32 s44, 0x58
	s_lshr_b32 s45, s43, 3
	s_add_i32 s44, s44, s45
	s_cmpk_ge_i32 s44, 176
	s_cselect_b32 s45, 1, 0
	s_cmpk_ge_i32 s44, 352
	s_cselect_b32 s98, 1, 0
	s_add_i32 s45, s45, s98
	s_cmpk_ge_i32 s44, 528
	s_cselect_b32 s98, 1, 0
	s_add_i32 s45, s45, s98
	s_mul_i32 s98, s45, 176
	s_sub_i32 s44, s44, s98
	s_and_b32 s98, s44, 7
	s_lshl_b32 s45, s45, 3
	s_add_i32 s45, s45, s98
	s_lshl_b32 s20, s45, 8
	s_lshr_b32 s44, s44, 3
	s_lshl_b32 s21, s44, 8
	s_mul_i32 s44, s20, 0x800
	s_add_u32 s44, s44, 0x8a44000
	s_add_u32 s22, s34, s44
	s_addc_u32 s23, s35, 0
	s_mul_i32 s44, s21, 0x800
	s_add_u32 s44, s44, 0x12a0000
	s_add_u32 s24, s34, s44
	s_addc_u32 s25, s35, 0
	s_branch .Lgl_havenext_ffnup1
